# row phases: split-K partial loads of the ctx rows through an 8-deep register ring with counted waits (on top of the LDS-DMA attention variant)
# speedup vs baseline: 1.0116x; 1.0116x over previous
; __device__ __forceinline__ void phase_rows(const Params& p, const RowArgs& a, int G, int wave, int lane) {
;     ...
;                 const float* part = (const float*)p.out;
; #pragma unroll
;                 for (int u = 0; u < 2; ++u)
; #pragma unroll
;                     for (int j = 0; j < 4; ++j) { const float* pp = part + (size_t)(m0 + u - ML) * DM + 8 * lane + 512 * (j >> 1) + 4 * (j & 1); f32x4 s = *(const f32x4*)pp;
; #pragma unroll
;                         for (int k = 1; k < pg8::KSPLIT; ++k) s += *(const f32x4*)(pp + (size_t)k * MC * DM);
;                         y[u][j] = s; }
.LBB0_210:
	s_cmp_ge_i32 s11, s19
	s_mov_b64 s[0:1], -1
	s_cbranch_scc1 .LBB0_204
	s_lshl_b32 s4, s11, 1
	s_cmpk_lt_i32 s11, 0x4000
	s_cselect_b64 s[0:1], -1, 0
	s_ashr_i32 s5, s4, 31
	s_add_i32 s30, s4, 0xffff8000
	s_cmpk_gt_i32 s11, 0x3fff
	s_cselect_b64 s[8:9], -1, 0
	s_and_b64 s[6:7], s[8:9], exec
	s_cselect_b32 s7, 0, s5
	s_cselect_b32 s6, s30, s4
	s_cselect_b32 s23, s99, s79
	s_cselect_b32 s26, s98, s78
	s_lshl_b64 s[24:25], s[6:7], 11
	s_add_u32 s24, s26, s24
	s_addc_u32 s25, s23, s25
	global_load_dwordx4 v[116:119], v170, s[24:25] nt
	global_load_dwordx4 v[112:115], v170, s[24:25] offset:1024 nt
	global_load_dwordx4 v[108:111], v170, s[24:25] offset:2048 nt
	global_load_dwordx4 v[104:107], v170, s[24:25] offset:3072 nt
	s_and_b64 vcc, exec, s[0:1]
	s_cbranch_vccnz .LBB0_213
	s_lshl_b64 s[24:25], s[30:31], 12
	v_lshl_add_u64 v[88:89], v[176:177], 0, s[24:25]
	v_mov_b32_e32 v200, v88
	v_mov_b32_e32 v201, v89
	v_add_co_u32_e32 v202, vcc, 0x800000, v200
	s_nop 1
	v_addc_co_u32_e32 v203, vcc, 0, v201, vcc
	v_add_co_u32_e32 v204, vcc, 0x800000, v202
	s_nop 1
	v_addc_co_u32_e32 v205, vcc, 0, v203, vcc
	v_add_co_u32_e32 v206, vcc, 0x800000, v204
	s_nop 1
	v_addc_co_u32_e32 v207, vcc, 0, v205, vcc
	v_add_co_u32_e32 v208, vcc, 0x800000, v206
	s_nop 1
	v_addc_co_u32_e32 v209, vcc, 0, v207, vcc
	v_add_co_u32_e32 v210, vcc, 0x800000, v208
	s_nop 1
	v_addc_co_u32_e32 v211, vcc, 0, v209, vcc
	v_add_co_u32_e32 v212, vcc, 0x800000, v210
	s_nop 1
	v_addc_co_u32_e32 v213, vcc, 0, v211, vcc
	v_add_co_u32_e32 v214, vcc, 0x800000, v212
	s_nop 1
	v_addc_co_u32_e32 v215, vcc, 0, v213, vcc
	global_load_dwordx4 v[216:219], v[200:201], off offset:16
	global_load_dwordx4 v[224:227], v[200:201], off
	global_load_dwordx4 v[228:231], v[202:203], off
	global_load_dwordx4 v[232:235], v[202:203], off offset:16
	global_load_dwordx4 v[236:239], v[204:205], off
	global_load_dwordx4 v[240:243], v[204:205], off offset:16
	global_load_dwordx4 v[244:247], v[206:207], off
	global_load_dwordx4 v[248:251], v[206:207], off offset:16
	v_add_co_u32_e32 v96, vcc, 0x800000, v88
	s_mov_b64 s[26:27], 0x800000
	v_addc_co_u32_e32 v97, vcc, 0, v89, vcc
	v_lshl_add_u64 v[94:95], v[88:89], 0, s[26:27]
	s_mov_b64 s[28:29], 0x1000000
	v_add_co_u32_e32 v122, vcc, 0x1000000, v88
	s_mov_b64 s[62:63], 0x1800000
	s_nop 0
	v_addc_co_u32_e32 v123, vcc, 0, v89, vcc
	v_add_co_u32_e32 v120, vcc, 0x1800000, v88
	v_lshl_add_u64 v[100:101], v[88:89], 0, s[62:63]
	s_nop 0
	v_addc_co_u32_e32 v121, vcc, 0, v89, vcc
	v_add_co_u32_e32 v102, vcc, 0x2000000, v88
	s_mov_b64 s[64:65], 0x2000000
	s_nop 0
	v_addc_co_u32_e32 v103, vcc, 0, v89, vcc
	v_add_co_u32_e32 v124, vcc, 0x2800000, v88
	s_mov_b64 s[68:69], 0x2800000
	s_nop 0
	v_addc_co_u32_e32 v125, vcc, 0, v89, vcc
	s_mov_b64 s[70:71], 0x3000000
	v_lshl_add_u64 v[142:143], v[88:89], 0, s[70:71]
	s_mov_b64 s[74:75], 0x3800000
	v_lshl_add_u64 v[146:147], v[88:89], 0, s[74:75]
	s_mov_b64 s[76:77], 0x800800
	s_mov_b64 s[40:41], s[34:35]
	s_mov_b64 s[34:35], 0x1000800
	s_mov_b64 s[86:87], 0x1800800
	s_mov_b64 s[94:95], 0x2000800
	s_mov_b64 s[14:15], 0x2800800
	s_mov_b32 s33, s96
	s_mov_b32 s39, s97
	s_mov_b64 s[96:97], 0x3000800
	s_mov_b64 s[36:37], 0x3800800
	s_add_i32 s30, s4, 0xffff8001
	s_lshl_b64 s[24:25], s[30:31], 12
	s_mov_b32 s23, 0x1000000
	s_waitcnt vmcnt(6)
	v_mov_b32_e32 v80, v224
	v_mov_b32_e32 v81, v225
	v_mov_b32_e32 v82, v226
	v_mov_b32_e32 v83, v227
	global_load_dwordx4 v[224:227], v[208:209], off
	s_waitcnt vmcnt(6)
	v_mov_b32_e32 v90, v228
	v_mov_b32_e32 v91, v229
	v_mov_b32_e32 v92, v230
	v_mov_b32_e32 v93, v231
	global_load_dwordx4 v[228:231], v[208:209], off offset:16
	v_pk_add_f32 v[98:99], v[82:83], v[92:93]
	v_lshl_add_u64 v[92:93], v[88:89], 0, s[28:29]
	v_pk_add_f32 v[90:91], v[80:81], v[90:91]
	s_nop 0
	s_waitcnt vmcnt(9)
	v_mov_b32_e32 v84, v216
	v_mov_b32_e32 v85, v217
	v_mov_b32_e32 v86, v218
	v_mov_b32_e32 v87, v219
	global_load_dwordx4 v[216:219], v[210:211], off
	s_waitcnt vmcnt(7)
	v_mov_b32_e32 v126, v232
	v_mov_b32_e32 v127, v233
	v_mov_b32_e32 v128, v234
	v_mov_b32_e32 v129, v235
	global_load_dwordx4 v[232:235], v[210:211], off offset:16
	v_pk_add_f32 v[86:87], v[86:87], v[128:129]
	v_pk_add_f32 v[84:85], v[84:85], v[126:127]
	s_waitcnt vmcnt(7)
	v_mov_b32_e32 v80, v236
	v_mov_b32_e32 v81, v237
	v_mov_b32_e32 v82, v238
	v_mov_b32_e32 v83, v239
	global_load_dwordx4 v[236:239], v[212:213], off
	v_pk_add_f32 v[98:99], v[98:99], v[82:83]
	v_pk_add_f32 v[90:91], v[90:91], v[80:81]
	v_lshl_add_u64 v[100:101], v[88:89], 0, s[64:65]
	s_waitcnt vmcnt(7)
	v_mov_b32_e32 v92, v240
	v_mov_b32_e32 v93, v241
	v_mov_b32_e32 v94, v242
	v_mov_b32_e32 v95, v243
	global_load_dwordx4 v[240:243], v[212:213], off offset:16
	v_pk_add_f32 v[86:87], v[86:87], v[94:95]
	v_pk_add_f32 v[84:85], v[84:85], v[92:93]
	s_waitcnt vmcnt(7)
	v_mov_b32_e32 v80, v244
	v_mov_b32_e32 v81, v245
	v_mov_b32_e32 v82, v246
	v_mov_b32_e32 v83, v247
	global_load_dwordx4 v[244:247], v[214:215], off
	v_pk_add_f32 v[98:99], v[98:99], v[82:83]
	v_pk_add_f32 v[90:91], v[90:91], v[80:81]
	v_lshl_add_u64 v[100:101], v[88:89], 0, s[68:69]
	s_waitcnt vmcnt(7)
	v_mov_b32_e32 v130, v248
	v_mov_b32_e32 v131, v249
	v_mov_b32_e32 v132, v250
	v_mov_b32_e32 v133, v251
	global_load_dwordx4 v[248:251], v[214:215], off offset:16
	v_pk_add_f32 v[86:87], v[86:87], v[132:133]
	v_pk_add_f32 v[84:85], v[84:85], v[130:131]
	s_waitcnt vmcnt(7)
	v_mov_b32_e32 v80, v224
	v_mov_b32_e32 v81, v225
	v_mov_b32_e32 v82, v226
	v_mov_b32_e32 v83, v227
	global_load_dwordx4 v[224:227], v[200:201], off offset:2064
	v_pk_add_f32 v[98:99], v[98:99], v[82:83]
	v_pk_add_f32 v[90:91], v[90:91], v[80:81]
	v_add_co_u32_e32 v100, vcc, 0x3000000, v88
	s_waitcnt vmcnt(7)
; __device__ __forceinline__ void phase_rows(const Params& p, const RowArgs& a, int G, int wave, int lane) {
;     ...
;                 const float* part = (const float*)p.out;
; #pragma unroll
;                 for (int u = 0; u < 2; ++u)
; #pragma unroll
;                     for (int j = 0; j < 4; ++j) { const float* pp = part + (size_t)(m0 + u - ML) * DM + 8 * lane + 512 * (j >> 1) + 4 * (j & 1); f32x4 s = *(const f32x4*)pp;
; #pragma unroll
;                         for (int k = 1; k < pg8::KSPLIT; ++k) s += *(const f32x4*)(pp + (size_t)k * MC * DM);
;                         y[u][j] = s; }
	v_mov_b32_e32 v134, v228
	v_mov_b32_e32 v135, v229
	v_mov_b32_e32 v136, v230
	v_mov_b32_e32 v137, v231
	global_load_dwordx4 v[228:231], v[200:201], off offset:2048
	v_pk_add_f32 v[86:87], v[86:87], v[136:137]
	v_addc_co_u32_e32 v101, vcc, 0, v89, vcc
	v_pk_add_f32 v[84:85], v[84:85], v[134:135]
	s_waitcnt vmcnt(7)
	v_mov_b32_e32 v80, v216
	v_mov_b32_e32 v81, v217
	v_mov_b32_e32 v82, v218
	v_mov_b32_e32 v83, v219
	global_load_dwordx4 v[216:219], v[202:203], off offset:2048
	v_pk_add_f32 v[98:99], v[98:99], v[82:83]
	v_pk_add_f32 v[90:91], v[90:91], v[80:81]
	s_nop 0
	s_waitcnt vmcnt(7)
	v_mov_b32_e32 v138, v232
	v_mov_b32_e32 v139, v233
	v_mov_b32_e32 v140, v234
	v_mov_b32_e32 v141, v235
	global_load_dwordx4 v[232:235], v[202:203], off offset:2064
	v_pk_add_f32 v[84:85], v[84:85], v[138:139]
	v_pk_add_f32 v[86:87], v[86:87], v[140:141]
	s_waitcnt vmcnt(7)
	v_mov_b32_e32 v80, v236
	v_mov_b32_e32 v81, v237
	v_mov_b32_e32 v82, v238
	v_mov_b32_e32 v83, v239
	global_load_dwordx4 v[236:239], v[204:205], off offset:2048
	v_pk_add_f32 v[150:151], v[90:91], v[80:81]
	v_add_co_u32_e32 v90, vcc, 0x3800000, v88
	v_pk_add_f32 v[98:99], v[98:99], v[82:83]
	s_nop 0
	v_addc_co_u32_e32 v91, vcc, 0, v89, vcc
	s_nop 0
	s_nop 0
	s_waitcnt vmcnt(7)
	v_mov_b32_e32 v142, v240
	v_mov_b32_e32 v143, v241
	v_mov_b32_e32 v144, v242
	v_mov_b32_e32 v145, v243
	global_load_dwordx4 v[240:243], v[204:205], off offset:2064
	v_pk_add_f32 v[84:85], v[84:85], v[142:143]
	v_pk_add_f32 v[86:87], v[86:87], v[144:145]
	s_waitcnt vmcnt(7)
	v_mov_b32_e32 v80, v244
	v_mov_b32_e32 v81, v245
	v_mov_b32_e32 v82, v246
	v_mov_b32_e32 v83, v247
	global_load_dwordx4 v[244:247], v[206:207], off offset:2048
	v_pk_add_f32 v[82:83], v[98:99], v[82:83]
	v_lshl_add_u64 v[98:99], v[88:89], 0, s[76:77]
	s_nop 0
	s_waitcnt vmcnt(7)
	v_mov_b32_e32 v146, v248
	v_mov_b32_e32 v147, v249
	v_mov_b32_e32 v148, v250
	v_mov_b32_e32 v149, v251
	global_load_dwordx4 v[248:251], v[206:207], off offset:2064
	v_pk_add_f32 v[86:87], v[86:87], v[148:149]
	v_pk_add_f32 v[84:85], v[84:85], v[146:147]
	v_pk_add_f32 v[80:81], v[150:151], v[80:81]
	s_waitcnt vmcnt(6)
	v_mov_b32_e32 v126, v228
	v_mov_b32_e32 v127, v229
	v_mov_b32_e32 v128, v230
	v_mov_b32_e32 v129, v231
	global_load_dwordx4 v[228:231], v[208:209], off offset:2048
	s_waitcnt vmcnt(6)
	v_mov_b32_e32 v130, v216
	v_mov_b32_e32 v131, v217
	v_mov_b32_e32 v132, v218
	v_mov_b32_e32 v133, v219
	global_load_dwordx4 v[216:219], v[208:209], off offset:2064
	v_pk_add_f32 v[136:137], v[126:127], v[130:131]
	v_lshl_add_u64 v[130:131], v[88:89], 0, s[34:35]
	v_pk_add_f32 v[134:135], v[128:129], v[132:133]
	s_nop 0
	s_waitcnt vmcnt(9)
	v_mov_b32_e32 v92, v224
	v_mov_b32_e32 v93, v225
	v_mov_b32_e32 v94, v226
	v_mov_b32_e32 v95, v227
	global_load_dwordx4 v[224:227], v[210:211], off offset:2048
	s_waitcnt vmcnt(7)
	v_mov_b32_e32 v96, v232
	v_mov_b32_e32 v97, v233
	v_mov_b32_e32 v98, v234
	v_mov_b32_e32 v99, v235
	global_load_dwordx4 v[232:235], v[210:211], off offset:2064
	v_pk_add_f32 v[92:93], v[92:93], v[96:97]
	v_pk_add_f32 v[94:95], v[94:95], v[98:99]
	s_waitcnt vmcnt(7)
	v_mov_b32_e32 v126, v236
	v_mov_b32_e32 v127, v237
	v_mov_b32_e32 v128, v238
	v_mov_b32_e32 v129, v239
	global_load_dwordx4 v[236:239], v[212:213], off offset:2048
	v_pk_add_f32 v[136:137], v[136:137], v[126:127]
	v_lshl_add_u64 v[126:127], v[88:89], 0, s[86:87]
	v_pk_add_f32 v[134:135], v[134:135], v[128:129]
	s_nop 0
	s_waitcnt vmcnt(7)
	v_mov_b32_e32 v130, v240
	v_mov_b32_e32 v131, v241
	v_mov_b32_e32 v132, v242
	v_mov_b32_e32 v133, v243
	global_load_dwordx4 v[240:243], v[212:213], off offset:2064
	v_pk_add_f32 v[92:93], v[92:93], v[130:131]
	v_pk_add_f32 v[94:95], v[94:95], v[132:133]
	s_waitcnt vmcnt(7)
	v_mov_b32_e32 v120, v244
	v_mov_b32_e32 v121, v245
	v_mov_b32_e32 v122, v246
	v_mov_b32_e32 v123, v247
	global_load_dwordx4 v[244:247], v[214:215], off offset:2048
	v_pk_add_f32 v[138:139], v[134:135], v[122:123]
	v_lshl_add_u64 v[134:135], v[88:89], 0, s[94:95]
	v_pk_add_f32 v[140:141], v[136:137], v[120:121]
	s_nop 0
	s_waitcnt vmcnt(7)
	v_mov_b32_e32 v126, v248
	v_mov_b32_e32 v127, v249
	v_mov_b32_e32 v128, v250
	v_mov_b32_e32 v129, v251
	global_load_dwordx4 v[248:251], v[214:215], off offset:2064
	v_pk_add_f32 v[92:93], v[92:93], v[126:127]
	v_pk_add_f32 v[94:95], v[94:95], v[128:129]
	s_waitcnt vmcnt(7)
	v_mov_b32_e32 v120, v228
	v_mov_b32_e32 v121, v229
	v_mov_b32_e32 v122, v230
	v_mov_b32_e32 v123, v231
	v_pk_add_f32 v[102:103], v[138:139], v[122:123]
	v_lshl_add_u64 v[138:139], v[88:89], 0, s[14:15]
	v_pk_add_f32 v[142:143], v[140:141], v[120:121]
	s_nop 0
	s_waitcnt vmcnt(6)
	v_mov_b32_e32 v134, v216
	v_mov_b32_e32 v135, v217
	v_mov_b32_e32 v136, v218
	v_mov_b32_e32 v137, v219
	v_pk_add_f32 v[92:93], v[92:93], v[134:135]
	v_pk_add_f32 v[94:95], v[94:95], v[136:137]
	s_waitcnt vmcnt(5)
	v_mov_b32_e32 v120, v224
	v_mov_b32_e32 v121, v225
	v_mov_b32_e32 v122, v226
	v_mov_b32_e32 v123, v227
	v_pk_add_f32 v[142:143], v[142:143], v[120:121]
	v_lshl_add_u64 v[120:121], v[88:89], 0, s[96:97]
	v_pk_add_f32 v[124:125], v[102:103], v[122:123]
	s_nop 0
	s_waitcnt vmcnt(4)
	v_mov_b32_e32 v138, v232
	v_mov_b32_e32 v139, v233
	v_mov_b32_e32 v140, v234
	v_mov_b32_e32 v141, v235
	v_pk_add_f32 v[92:93], v[92:93], v[138:139]
	v_pk_add_f32 v[94:95], v[94:95], v[140:141]
	s_waitcnt vmcnt(3)
	v_mov_b32_e32 v100, v236
	v_mov_b32_e32 v101, v237
	v_mov_b32_e32 v102, v238
	v_mov_b32_e32 v103, v239
	v_pk_add_f32 v[142:143], v[142:143], v[100:101]
	v_lshl_add_u64 v[100:101], v[88:89], 0, s[36:37]
	v_pk_add_f32 v[124:125], v[124:125], v[102:103]
	s_nop 0
	s_waitcnt vmcnt(2)
; __device__ __forceinline__ void phase_rows(const Params& p, const RowArgs& a, int G, int wave, int lane) {
;     ...
;                 const float* part = (const float*)p.out;
; #pragma unroll
;                 for (int u = 0; u < 2; ++u)
; #pragma unroll
;                     for (int j = 0; j < 4; ++j) { const float* pp = part + (size_t)(m0 + u - ML) * DM + 8 * lane + 512 * (j >> 1) + 4 * (j & 1); f32x4 s = *(const f32x4*)pp;
; #pragma unroll
;                         for (int k = 1; k < pg8::KSPLIT; ++k) s += *(const f32x4*)(pp + (size_t)k * MC * DM);
;                         y[u][j] = s; }
	v_mov_b32_e32 v120, v240
	v_mov_b32_e32 v121, v241
	v_mov_b32_e32 v122, v242
	v_mov_b32_e32 v123, v243
	v_pk_add_f32 v[92:93], v[92:93], v[120:121]
	v_lshl_add_u64 v[120:121], v[176:177], 0, s[24:25]
	v_pk_add_f32 v[94:95], v[94:95], v[122:123]
	v_add_co_u32_e32 v128, vcc, s55, v120
	v_lshl_add_u64 v[126:127], v[120:121], 0, s[26:27]
	s_nop 0
	v_addc_co_u32_e32 v129, vcc, 0, v121, vcc
	v_add_co_u32_e32 v132, vcc, s23, v120
	s_mov_b32 s23, 0x1800000
	s_nop 0
	v_addc_co_u32_e32 v133, vcc, 0, v121, vcc
	v_add_co_u32_e32 v136, vcc, s23, v120
	v_lshl_add_u64 v[134:135], v[120:121], 0, s[62:63]
	s_nop 0
	v_addc_co_u32_e32 v137, vcc, 0, v121, vcc
	s_brev_b32 s23, 64
	s_waitcnt vmcnt(1)
	v_mov_b32_e32 v88, v244
	v_mov_b32_e32 v89, v245
	v_mov_b32_e32 v90, v246
	v_mov_b32_e32 v91, v247
	v_pk_add_f32 v[90:91], v[124:125], v[90:91]
	s_waitcnt vmcnt(0)
	v_mov_b32_e32 v100, v248
	v_mov_b32_e32 v101, v249
	v_mov_b32_e32 v102, v250
	v_mov_b32_e32 v103, v251
	v_pk_add_f32 v[94:95], v[94:95], v[102:103]
	v_pk_add_f32 v[92:93], v[92:93], v[100:101]
	v_add_co_u32_e32 v200, vcc, 0x1000, v200
	s_nop 1
	v_addc_co_u32_e32 v201, vcc, 0, v201, vcc
	v_add_co_u32_e32 v202, vcc, 0x1000, v202
	s_nop 1
	v_addc_co_u32_e32 v203, vcc, 0, v203, vcc
	v_add_co_u32_e32 v204, vcc, 0x1000, v204
	s_nop 1
	v_addc_co_u32_e32 v205, vcc, 0, v205, vcc
	v_add_co_u32_e32 v206, vcc, 0x1000, v206
	s_nop 1
	v_addc_co_u32_e32 v207, vcc, 0, v207, vcc
	v_add_co_u32_e32 v208, vcc, 0x1000, v208
	s_nop 1
	v_addc_co_u32_e32 v209, vcc, 0, v209, vcc
	v_add_co_u32_e32 v210, vcc, 0x1000, v210
	s_nop 1
	v_addc_co_u32_e32 v211, vcc, 0, v211, vcc
	v_add_co_u32_e32 v212, vcc, 0x1000, v212
	s_nop 1
	v_addc_co_u32_e32 v213, vcc, 0, v213, vcc
	v_add_co_u32_e32 v214, vcc, 0x1000, v214
	s_nop 1
	v_addc_co_u32_e32 v215, vcc, 0, v215, vcc
	global_load_dwordx4 v[216:219], v[200:201], off offset:16
	global_load_dwordx4 v[224:227], v[200:201], off
	global_load_dwordx4 v[228:231], v[202:203], off
	global_load_dwordx4 v[232:235], v[202:203], off offset:16
	global_load_dwordx4 v[236:239], v[204:205], off
	global_load_dwordx4 v[240:243], v[204:205], off offset:16
	global_load_dwordx4 v[244:247], v[206:207], off
	global_load_dwordx4 v[248:251], v[206:207], off offset:16
	v_pk_add_f32 v[88:89], v[142:143], v[88:89]
	v_lshl_add_u64 v[142:143], v[120:121], 0, s[64:65]
	s_waitcnt vmcnt(6)
	v_mov_b32_e32 v96, v224
	v_mov_b32_e32 v97, v225
	v_mov_b32_e32 v98, v226
	v_mov_b32_e32 v99, v227
	global_load_dwordx4 v[224:227], v[208:209], off
	s_waitcnt vmcnt(6)
	v_mov_b32_e32 v122, v228
	v_mov_b32_e32 v123, v229
	v_mov_b32_e32 v124, v230
	v_mov_b32_e32 v125, v231
	global_load_dwordx4 v[228:231], v[208:209], off offset:16
	v_pk_add_f32 v[130:131], v[98:99], v[124:125]
	v_lshl_add_u64 v[124:125], v[120:121], 0, s[28:29]
	v_pk_add_f32 v[122:123], v[96:97], v[122:123]
	s_nop 0
	s_waitcnt vmcnt(9)
	v_mov_b32_e32 v100, v216
	v_mov_b32_e32 v101, v217
	v_mov_b32_e32 v102, v218
	v_mov_b32_e32 v103, v219
	global_load_dwordx4 v[216:219], v[210:211], off
	s_waitcnt vmcnt(7)
	v_mov_b32_e32 v138, v232
	v_mov_b32_e32 v139, v233
	v_mov_b32_e32 v140, v234
	v_mov_b32_e32 v141, v235
	global_load_dwordx4 v[232:235], v[210:211], off offset:16
	v_pk_add_f32 v[102:103], v[102:103], v[140:141]
	v_pk_add_f32 v[100:101], v[100:101], v[138:139]
	s_waitcnt vmcnt(7)
	v_mov_b32_e32 v96, v236
	v_mov_b32_e32 v97, v237
	v_mov_b32_e32 v98, v238
	v_mov_b32_e32 v99, v239
	global_load_dwordx4 v[236:239], v[212:213], off
	v_pk_add_f32 v[130:131], v[130:131], v[98:99]
	v_pk_add_f32 v[122:123], v[122:123], v[96:97]
	s_waitcnt vmcnt(7)
	v_mov_b32_e32 v124, v240
	v_mov_b32_e32 v125, v241
	v_mov_b32_e32 v126, v242
	v_mov_b32_e32 v127, v243
	global_load_dwordx4 v[240:243], v[212:213], off offset:16
	v_pk_add_f32 v[102:103], v[102:103], v[126:127]
	v_pk_add_f32 v[100:101], v[100:101], v[124:125]
	s_waitcnt vmcnt(7)
	v_mov_b32_e32 v96, v244
	v_mov_b32_e32 v97, v245
	v_mov_b32_e32 v98, v246
	v_mov_b32_e32 v99, v247
	global_load_dwordx4 v[244:247], v[214:215], off
	v_pk_add_f32 v[134:135], v[122:123], v[96:97]
	v_add_co_u32_e32 v122, vcc, s23, v120
	v_pk_add_f32 v[130:131], v[130:131], v[98:99]
	s_nop 0
	v_addc_co_u32_e32 v123, vcc, 0, v121, vcc
	s_mov_b32 s23, 0x2800000
	v_add_co_u32_e32 v144, vcc, s23, v120
	v_lshl_add_u64 v[142:143], v[120:121], 0, s[68:69]
	s_nop 0
	v_addc_co_u32_e32 v145, vcc, 0, v121, vcc
	s_mov_b32 s23, 0x3000000
	v_add_co_u32_e32 v148, vcc, s23, v120
	s_mov_b32 s23, 0x3800000
	s_nop 0
	v_addc_co_u32_e32 v149, vcc, 0, v121, vcc
	v_add_co_u32_e32 v152, vcc, s23, v120
	s_waitcnt vmcnt(7)
	v_mov_b32_e32 v178, v248
	v_mov_b32_e32 v179, v249
	v_mov_b32_e32 v180, v250
	v_mov_b32_e32 v181, v251
	global_load_dwordx4 v[248:251], v[214:215], off offset:16
	v_pk_add_f32 v[102:103], v[102:103], v[180:181]
	v_addc_co_u32_e32 v153, vcc, 0, v121, vcc
	v_pk_add_f32 v[100:101], v[100:101], v[178:179]
	s_waitcnt vmcnt(7)
	v_mov_b32_e32 v96, v224
	v_mov_b32_e32 v97, v225
	v_mov_b32_e32 v98, v226
	v_mov_b32_e32 v99, v227
	global_load_dwordx4 v[224:227], v[200:201], off offset:2064
	v_pk_add_f32 v[130:131], v[130:131], v[98:99]
	v_pk_add_f32 v[134:135], v[134:135], v[96:97]
	v_lshl_add_u64 v[142:143], v[120:121], 0, s[70:71]
	s_waitcnt vmcnt(7)
	v_mov_b32_e32 v182, v228
	v_mov_b32_e32 v183, v229
	v_mov_b32_e32 v184, v230
	v_mov_b32_e32 v185, v231
	global_load_dwordx4 v[228:231], v[200:201], off offset:2048
	v_pk_add_f32 v[100:101], v[100:101], v[182:183]
	v_pk_add_f32 v[102:103], v[102:103], v[184:185]
	s_waitcnt vmcnt(7)
; __device__ __forceinline__ void phase_rows(const Params& p, const RowArgs& a, int G, int wave, int lane) {
;     ...
;                 const float* part = (const float*)p.out;
; #pragma unroll
;                 for (int u = 0; u < 2; ++u)
; #pragma unroll
;                     for (int j = 0; j < 4; ++j) { const float* pp = part + (size_t)(m0 + u - ML) * DM + 8 * lane + 512 * (j >> 1) + 4 * (j & 1); f32x4 s = *(const f32x4*)pp;
; #pragma unroll
;                         for (int k = 1; k < pg8::KSPLIT; ++k) s += *(const f32x4*)(pp + (size_t)k * MC * DM);
;                         y[u][j] = s; }
	v_mov_b32_e32 v96, v216
	v_mov_b32_e32 v97, v217
	v_mov_b32_e32 v98, v218
	v_mov_b32_e32 v99, v219
	global_load_dwordx4 v[216:219], v[202:203], off offset:2048
	v_pk_add_f32 v[130:131], v[130:131], v[98:99]
	v_pk_add_f32 v[134:135], v[134:135], v[96:97]
	v_lshl_add_u64 v[142:143], v[120:121], 0, s[74:75]
	s_waitcnt vmcnt(7)
	v_mov_b32_e32 v186, v232
	v_mov_b32_e32 v187, v233
	v_mov_b32_e32 v188, v234
	v_mov_b32_e32 v189, v235
	global_load_dwordx4 v[232:235], v[202:203], off offset:2064
	v_pk_add_f32 v[102:103], v[102:103], v[188:189]
	v_pk_add_f32 v[100:101], v[100:101], v[186:187]
	s_waitcnt vmcnt(7)
	v_mov_b32_e32 v96, v236
	v_mov_b32_e32 v97, v237
	v_mov_b32_e32 v98, v238
	v_mov_b32_e32 v99, v239
	global_load_dwordx4 v[236:239], v[204:205], off offset:2048
	v_pk_add_f32 v[130:131], v[130:131], v[98:99]
	v_pk_add_f32 v[134:135], v[134:135], v[96:97]
	s_waitcnt vmcnt(7)
	v_mov_b32_e32 v190, v240
	v_mov_b32_e32 v191, v241
	v_mov_b32_e32 v192, v242
	v_mov_b32_e32 v193, v243
	global_load_dwordx4 v[240:243], v[204:205], off offset:2064
	v_pk_add_f32 v[102:103], v[102:103], v[192:193]
	v_pk_add_f32 v[100:101], v[100:101], v[190:191]
	s_waitcnt vmcnt(7)
	v_mov_b32_e32 v96, v244
	v_mov_b32_e32 v97, v245
	v_mov_b32_e32 v98, v246
	v_mov_b32_e32 v99, v247
	global_load_dwordx4 v[244:247], v[206:207], off offset:2048
	v_pk_add_f32 v[98:99], v[130:131], v[98:99]
	v_lshl_add_u64 v[130:131], v[120:121], 0, s[76:77]
	s_nop 0
	v_pk_add_f32 v[96:97], v[134:135], v[96:97]
	v_lshl_add_u64 v[134:135], v[120:121], 0, s[34:35]
	s_waitcnt vmcnt(7)
	v_mov_b32_e32 v194, v248
	v_mov_b32_e32 v195, v249
	v_mov_b32_e32 v196, v250
	v_mov_b32_e32 v197, v251
	global_load_dwordx4 v[248:251], v[206:207], off offset:2064
	v_pk_add_f32 v[102:103], v[102:103], v[196:197]
	v_pk_add_f32 v[100:101], v[100:101], v[194:195]
	s_mov_b64 s[34:35], s[40:41]
	s_waitcnt vmcnt(6)
	v_mov_b32_e32 v138, v228
	v_mov_b32_e32 v139, v229
	v_mov_b32_e32 v140, v230
	v_mov_b32_e32 v141, v231
	global_load_dwordx4 v[228:231], v[208:209], off offset:2048
	s_waitcnt vmcnt(6)
	v_mov_b32_e32 v178, v216
	v_mov_b32_e32 v179, v217
	v_mov_b32_e32 v180, v218
	v_mov_b32_e32 v181, v219
	global_load_dwordx4 v[216:219], v[208:209], off offset:2064
	v_pk_add_f32 v[142:143], v[140:141], v[180:181]
	v_pk_add_f32 v[146:147], v[138:139], v[178:179]
	s_nop 0
	s_waitcnt vmcnt(9)
	v_mov_b32_e32 v124, v224
	v_mov_b32_e32 v125, v225
	v_mov_b32_e32 v126, v226
	v_mov_b32_e32 v127, v227
	global_load_dwordx4 v[224:227], v[210:211], off offset:2048
	s_waitcnt vmcnt(7)
	v_mov_b32_e32 v128, v232
	v_mov_b32_e32 v129, v233
	v_mov_b32_e32 v130, v234
	v_mov_b32_e32 v131, v235
	global_load_dwordx4 v[232:235], v[210:211], off offset:2064
	v_pk_add_f32 v[126:127], v[126:127], v[130:131]
	v_pk_add_f32 v[124:125], v[124:125], v[128:129]
	s_waitcnt vmcnt(7)
	v_mov_b32_e32 v138, v236
	v_mov_b32_e32 v139, v237
	v_mov_b32_e32 v140, v238
	v_mov_b32_e32 v141, v239
	global_load_dwordx4 v[236:239], v[212:213], off offset:2048
	v_pk_add_f32 v[146:147], v[146:147], v[138:139]
	v_lshl_add_u64 v[138:139], v[120:121], 0, s[86:87]
	v_pk_add_f32 v[150:151], v[142:143], v[140:141]
	s_nop 0
	s_waitcnt vmcnt(7)
	v_mov_b32_e32 v132, v240
	v_mov_b32_e32 v133, v241
	v_mov_b32_e32 v134, v242
	v_mov_b32_e32 v135, v243
	global_load_dwordx4 v[240:243], v[212:213], off offset:2064
	v_pk_add_f32 v[126:127], v[126:127], v[134:135]
	v_pk_add_f32 v[124:125], v[124:125], v[132:133]
	s_mov_b32 s87, s38
	v_readlane_b32 s86, v255, 11
	s_waitcnt vmcnt(7)
	v_mov_b32_e32 v140, v244
	v_mov_b32_e32 v141, v245
	v_mov_b32_e32 v142, v246
	v_mov_b32_e32 v143, v247
	global_load_dwordx4 v[244:247], v[214:215], off offset:2048
	v_pk_add_f32 v[146:147], v[146:147], v[140:141]
	v_lshl_add_u64 v[140:141], v[120:121], 0, s[94:95]
	v_pk_add_f32 v[150:151], v[150:151], v[142:143]
	s_nop 0
	s_waitcnt vmcnt(7)
	v_mov_b32_e32 v136, v248
	v_mov_b32_e32 v137, v249
	v_mov_b32_e32 v138, v250
	v_mov_b32_e32 v139, v251
	global_load_dwordx4 v[248:251], v[214:215], off offset:2064
	v_pk_add_f32 v[126:127], v[126:127], v[138:139]
	v_pk_add_f32 v[124:125], v[124:125], v[136:137]
	v_readlane_b32 s94, v255, 27
	v_readlane_b32 s95, v255, 28
	s_waitcnt vmcnt(7)
	v_mov_b32_e32 v178, v228
	v_mov_b32_e32 v179, v229
	v_mov_b32_e32 v180, v230
	v_mov_b32_e32 v181, v231
	v_pk_add_f32 v[122:123], v[150:151], v[180:181]
	v_pk_add_f32 v[150:151], v[146:147], v[178:179]
	v_lshl_add_u64 v[146:147], v[120:121], 0, s[14:15]
	s_nop 0
	s_waitcnt vmcnt(6)
	v_mov_b32_e32 v140, v216
	v_mov_b32_e32 v141, v217
	v_mov_b32_e32 v142, v218
	v_mov_b32_e32 v143, v219
	v_pk_add_f32 v[126:127], v[126:127], v[142:143]
	v_pk_add_f32 v[124:125], v[124:125], v[140:141]
	s_waitcnt vmcnt(5)
	v_mov_b32_e32 v178, v224
	v_mov_b32_e32 v179, v225
	v_mov_b32_e32 v180, v226
	v_mov_b32_e32 v181, v227
	v_pk_add_f32 v[154:155], v[150:151], v[178:179]
	v_lshl_add_u64 v[150:151], v[120:121], 0, s[96:97]
	v_pk_add_f32 v[122:123], v[122:123], v[180:181]
	s_nop 0
	s_waitcnt vmcnt(4)
	v_mov_b32_e32 v144, v232
	v_mov_b32_e32 v145, v233
	v_mov_b32_e32 v146, v234
	v_mov_b32_e32 v147, v235
	v_pk_add_f32 v[126:127], v[126:127], v[146:147]
	v_pk_add_f32 v[124:125], v[124:125], v[144:145]
	s_mov_b32 s97, s39
	s_mov_b32 s96, s33
	s_waitcnt vmcnt(3)
	v_mov_b32_e32 v180, v236
	v_mov_b32_e32 v181, v237
	v_mov_b32_e32 v182, v238
	v_mov_b32_e32 v183, v239
	v_pk_add_f32 v[180:181], v[154:155], v[180:181]
	v_lshl_add_u64 v[154:155], v[120:121], 0, s[36:37]
	v_pk_add_f32 v[178:179], v[122:123], v[182:183]
	s_nop 0
	s_waitcnt vmcnt(2)
	v_mov_b32_e32 v148, v240
	v_mov_b32_e32 v149, v241
	v_mov_b32_e32 v150, v242
	v_mov_b32_e32 v151, v243
	v_pk_add_f32 v[126:127], v[126:127], v[150:151]
	v_pk_add_f32 v[124:125], v[124:125], v[148:149]
	s_waitcnt vmcnt(1)
	v_mov_b32_e32 v120, v244
	v_mov_b32_e32 v121, v245
	v_mov_b32_e32 v122, v246
	v_mov_b32_e32 v123, v247
	v_pk_add_f32 v[122:123], v[178:179], v[122:123]
	v_pk_add_f32 v[120:121], v[180:181], v[120:121]
	s_waitcnt vmcnt(0)
	v_mov_b32_e32 v152, v248
	v_mov_b32_e32 v153, v249
	v_mov_b32_e32 v154, v250
	v_mov_b32_e32 v155, v251
	v_pk_add_f32 v[126:127], v[126:127], v[154:155]
	v_pk_add_f32 v[124:125], v[124:125], v[152:153]

; __device__ __forceinline__ f32x4 bfx4_lo(u32x4 w) { return (f32x4){bf_lo(w.x), bf_hi(w.x), bf_lo(w.y), bf_hi(w.y)}; }
; __device__ __forceinline__ void phase_rows(const Params& p, const RowArgs& a, int G, int wave, int lane) {
;     ...
;         if (bmaj) mp = (it < ppw) ? (gw / wpb) * (SEQ / 2) + (gw % wpb) + it * wpb : ML / 2 + gw + (it - ppw) * NGW;
;         else mp = ((a.ctx_only && !bmaj) ? ML / 2 : 0) + gw + it * NGW;
;         if (mp >= a.nrows / 2) break;
;         const int m0 = 2 * mp; const bool isl = m0 < ML; const int rb = isl ? (m0 >> 12) : 8;
;         const bool use_y = a.has_y && !(a.lat_no_y && isl);
;         const size_t xoff = isl ? (size_t)m0 * DM : (size_t)(m0 - ML) * DM;
;         const void* xrb = isl ? a.xlat : a.xctx; void* xob = isl ? a.olat : a.octx;
;         bf16_t* xn = XN + (size_t)m0 * DM;
;         const size_t moff = (size_t)rb * NMOD;
;         f32x4 v[2][4], y[2][4];
;         if (a.xin_f32) {
; #pragma unroll
;             for (int u = 0; u < 2; ++u)
; #pragma unroll
;                 for (int j = 0; j < 4; ++j) v[u][j] = *(const f32x4*)((const float*)xrb + xoff + u * DM + 8 * lane + 512 * (j >> 1) + 4 * (j & 1));
;         } else {
; #pragma unroll
;             for (int u = 0; u < 2; ++u)
; #pragma unroll
;                 for (int jb = 0; jb < 2; ++jb) { const u32x4 xw = *(const u32x4*)((const bf16_t*)xrb + xoff + u * DM + 8 * lane + 512 * jb); v[u][2 * jb] = bfx4_lo(xw); v[u][2 * jb + 1] = bfx4_hi(xw); }
;         }
;         if (use_y) {
;             if (isl || !a.ctx_split) {
; #pragma unroll
;                 for (int u = 0; u < 2; ++u)
; #pragma unroll
;                     for (int jb = 0; jb < 2; ++jb) { const u32x4 yw = *(const u32x4*)(xn + u * DM + 8 * lane + 512 * jb); y[u][2 * jb] = bfx4_lo(yw); y[u][2 * jb + 1] = bfx4_hi(yw); }
;             } else {
;                 const float* part = (const float*)p.out;
; #pragma unroll
;                 for (int u = 0; u < 2; ++u)
; #pragma unroll
;                     for (int j = 0; j < 4; ++j) { const float* pp = part + (size_t)(m0 + u - ML) * DM + 8 * lane + 512 * (j >> 1) + 4 * (j & 1); f32x4 s = *(const f32x4*)pp;
; #pragma unroll
;                         for (int k = 1; k < pg8::KSPLIT; ++k) s += *(const f32x4*)(pp + (size_t)k * MC * DM);
;                         y[u][j] = s; }
.LBB0_327:
	s_cmpk_gt_i32 s11, 0x43ff
	s_mov_b64 s[0:1], -1
	s_cbranch_scc1 .LBB0_321
	s_lshl_b32 s4, s11, 1
	s_cmpk_lt_i32 s11, 0x4000
	s_cselect_b64 s[0:1], -1, 0
	s_ashr_i32 s5, s4, 31
	s_add_i32 s30, s4, 0xffff8000
	s_cmpk_gt_i32 s11, 0x3fff
	s_cselect_b64 s[8:9], -1, 0
	s_and_b64 s[6:7], s[8:9], exec
	s_cselect_b32 s7, 0, s5
	s_cselect_b32 s6, s30, s4
	s_cselect_b32 s21, s99, s79
	s_cselect_b32 s24, s98, s78
	s_lshl_b64 s[22:23], s[6:7], 11
	s_add_u32 s22, s24, s22
	s_addc_u32 s23, s21, s23
	global_load_dwordx4 v[116:119], v170, s[22:23] nt
	global_load_dwordx4 v[112:115], v170, s[22:23] offset:1024 nt
	global_load_dwordx4 v[108:111], v170, s[22:23] offset:2048 nt
	global_load_dwordx4 v[104:107], v170, s[22:23] offset:3072 nt
	s_and_b64 vcc, exec, s[0:1]
	s_cbranch_vccnz .LBB0_330
	s_lshl_b64 s[22:23], s[30:31], 12
	v_lshl_add_u64 v[88:89], v[176:177], 0, s[22:23]
	v_mov_b32_e32 v200, v88
	v_mov_b32_e32 v201, v89
	v_add_co_u32_e32 v202, vcc, 0x800000, v200
	s_nop 1
	v_addc_co_u32_e32 v203, vcc, 0, v201, vcc
	v_add_co_u32_e32 v204, vcc, 0x800000, v202
	s_nop 1
	v_addc_co_u32_e32 v205, vcc, 0, v203, vcc
	v_add_co_u32_e32 v206, vcc, 0x800000, v204
	s_nop 1
	v_addc_co_u32_e32 v207, vcc, 0, v205, vcc
	v_add_co_u32_e32 v208, vcc, 0x800000, v206
	s_nop 1
	v_addc_co_u32_e32 v209, vcc, 0, v207, vcc
	v_add_co_u32_e32 v210, vcc, 0x800000, v208
	s_nop 1
	v_addc_co_u32_e32 v211, vcc, 0, v209, vcc
	v_add_co_u32_e32 v212, vcc, 0x800000, v210
	s_nop 1
	v_addc_co_u32_e32 v213, vcc, 0, v211, vcc
	v_add_co_u32_e32 v214, vcc, 0x800000, v212
	s_nop 1
	v_addc_co_u32_e32 v215, vcc, 0, v213, vcc
	global_load_dwordx4 v[216:219], v[200:201], off offset:16
	global_load_dwordx4 v[224:227], v[200:201], off
	global_load_dwordx4 v[228:231], v[202:203], off
	global_load_dwordx4 v[232:235], v[202:203], off offset:16
	global_load_dwordx4 v[236:239], v[204:205], off
	global_load_dwordx4 v[240:243], v[204:205], off offset:16
	global_load_dwordx4 v[244:247], v[206:207], off
	global_load_dwordx4 v[248:251], v[206:207], off offset:16
	v_add_co_u32_e32 v96, vcc, 0x800000, v88
	s_mov_b64 s[24:25], 0x800000
	v_addc_co_u32_e32 v97, vcc, 0, v89, vcc
	v_lshl_add_u64 v[94:95], v[88:89], 0, s[24:25]
	s_mov_b64 s[26:27], 0x1000000
	v_add_co_u32_e32 v120, vcc, 0x1000000, v88
	s_mov_b64 s[28:29], 0x1800000
	s_nop 0
	v_addc_co_u32_e32 v121, vcc, 0, v89, vcc
	v_add_co_u32_e32 v122, vcc, 0x1800000, v88
	v_lshl_add_u64 v[100:101], v[88:89], 0, s[28:29]
	s_nop 0
	v_addc_co_u32_e32 v123, vcc, 0, v89, vcc
	v_add_co_u32_e32 v102, vcc, 0x2000000, v88
	s_mov_b64 s[34:35], 0x2000000
	s_nop 0
	v_addc_co_u32_e32 v103, vcc, 0, v89, vcc
	v_add_co_u32_e32 v124, vcc, 0x2800000, v88
	s_mov_b64 s[62:63], 0x2800000
	s_nop 0
	v_addc_co_u32_e32 v125, vcc, 0, v89, vcc
	s_mov_b64 s[64:65], 0x3000000
	v_lshl_add_u64 v[142:143], v[88:89], 0, s[64:65]
	s_mov_b64 s[68:69], 0x3800000
	v_lshl_add_u64 v[146:147], v[88:89], 0, s[68:69]
	s_mov_b64 s[70:71], 0x800800
	s_mov_b64 s[74:75], 0x1000800
	s_mov_b64 s[76:77], 0x1800800
	s_mov_b64 s[94:95], 0x2000800
	s_mov_b64 s[16:17], 0x2800800
	s_mov_b32 s38, s96
	s_mov_b64 s[96:97], 0x3000800
	s_mov_b64 s[36:37], 0x3800800
	s_add_i32 s30, s4, 0xffff8001
	s_lshl_b64 s[22:23], s[30:31], 12
	s_mov_b32 s21, 0x1000000
	s_waitcnt vmcnt(6)
	v_mov_b32_e32 v80, v224
	v_mov_b32_e32 v81, v225
	v_mov_b32_e32 v82, v226
	v_mov_b32_e32 v83, v227
	global_load_dwordx4 v[224:227], v[208:209], off
	s_waitcnt vmcnt(6)
	v_mov_b32_e32 v90, v228
	v_mov_b32_e32 v91, v229
	v_mov_b32_e32 v92, v230
	v_mov_b32_e32 v93, v231
	global_load_dwordx4 v[228:231], v[208:209], off offset:16
	v_pk_add_f32 v[98:99], v[82:83], v[92:93]
	v_lshl_add_u64 v[92:93], v[88:89], 0, s[26:27]
	v_pk_add_f32 v[90:91], v[80:81], v[90:91]
	s_nop 0
	s_waitcnt vmcnt(9)
	v_mov_b32_e32 v84, v216
	v_mov_b32_e32 v85, v217
	v_mov_b32_e32 v86, v218
	v_mov_b32_e32 v87, v219
	global_load_dwordx4 v[216:219], v[210:211], off
	s_waitcnt vmcnt(7)
	v_mov_b32_e32 v126, v232
	v_mov_b32_e32 v127, v233
	v_mov_b32_e32 v128, v234
	v_mov_b32_e32 v129, v235
	global_load_dwordx4 v[232:235], v[210:211], off offset:16
	v_pk_add_f32 v[86:87], v[86:87], v[128:129]
	v_pk_add_f32 v[84:85], v[84:85], v[126:127]
	s_waitcnt vmcnt(7)
	v_mov_b32_e32 v80, v236
	v_mov_b32_e32 v81, v237
	v_mov_b32_e32 v82, v238
	v_mov_b32_e32 v83, v239
	global_load_dwordx4 v[236:239], v[212:213], off
	v_pk_add_f32 v[98:99], v[98:99], v[82:83]
	v_pk_add_f32 v[90:91], v[90:91], v[80:81]
	v_lshl_add_u64 v[100:101], v[88:89], 0, s[34:35]
	s_waitcnt vmcnt(7)
	v_mov_b32_e32 v92, v240
	v_mov_b32_e32 v93, v241
	v_mov_b32_e32 v94, v242
	v_mov_b32_e32 v95, v243
	global_load_dwordx4 v[240:243], v[212:213], off offset:16
	v_pk_add_f32 v[86:87], v[86:87], v[94:95]
	v_pk_add_f32 v[84:85], v[84:85], v[92:93]
	s_waitcnt vmcnt(7)
	v_mov_b32_e32 v80, v244
	v_mov_b32_e32 v81, v245
	v_mov_b32_e32 v82, v246
	v_mov_b32_e32 v83, v247
	global_load_dwordx4 v[244:247], v[214:215], off
	v_pk_add_f32 v[98:99], v[98:99], v[82:83]
	v_pk_add_f32 v[90:91], v[90:91], v[80:81]
	v_lshl_add_u64 v[100:101], v[88:89], 0, s[62:63]
	s_waitcnt vmcnt(7)
	v_mov_b32_e32 v130, v248
	v_mov_b32_e32 v131, v249
	v_mov_b32_e32 v132, v250
	v_mov_b32_e32 v133, v251
	global_load_dwordx4 v[248:251], v[214:215], off offset:16
	v_pk_add_f32 v[86:87], v[86:87], v[132:133]
	v_pk_add_f32 v[84:85], v[84:85], v[130:131]
	s_waitcnt vmcnt(7)
	v_mov_b32_e32 v80, v224
	v_mov_b32_e32 v81, v225
	v_mov_b32_e32 v82, v226
	v_mov_b32_e32 v83, v227
	global_load_dwordx4 v[224:227], v[200:201], off offset:2064
	v_pk_add_f32 v[98:99], v[98:99], v[82:83]
	v_pk_add_f32 v[90:91], v[90:91], v[80:81]
	v_add_co_u32_e32 v100, vcc, 0x3000000, v88
	s_waitcnt vmcnt(7)
; __device__ __forceinline__ void phase_rows(const Params& p, const RowArgs& a, int G, int wave, int lane) {
;     ...
;                 const float* part = (const float*)p.out;
; #pragma unroll
;                 for (int u = 0; u < 2; ++u)
; #pragma unroll
;                     for (int j = 0; j < 4; ++j) { const float* pp = part + (size_t)(m0 + u - ML) * DM + 8 * lane + 512 * (j >> 1) + 4 * (j & 1); f32x4 s = *(const f32x4*)pp;
; #pragma unroll
;                         for (int k = 1; k < pg8::KSPLIT; ++k) s += *(const f32x4*)(pp + (size_t)k * MC * DM);
;                         y[u][j] = s; }
	v_mov_b32_e32 v134, v228
	v_mov_b32_e32 v135, v229
	v_mov_b32_e32 v136, v230
	v_mov_b32_e32 v137, v231
	global_load_dwordx4 v[228:231], v[200:201], off offset:2048
	v_pk_add_f32 v[86:87], v[86:87], v[136:137]
	v_addc_co_u32_e32 v101, vcc, 0, v89, vcc
	v_pk_add_f32 v[84:85], v[84:85], v[134:135]
	s_waitcnt vmcnt(7)
	v_mov_b32_e32 v80, v216
	v_mov_b32_e32 v81, v217
	v_mov_b32_e32 v82, v218
	v_mov_b32_e32 v83, v219
	global_load_dwordx4 v[216:219], v[202:203], off offset:2048
	v_pk_add_f32 v[98:99], v[98:99], v[82:83]
	v_pk_add_f32 v[90:91], v[90:91], v[80:81]
	s_nop 0
	s_waitcnt vmcnt(7)
	v_mov_b32_e32 v138, v232
	v_mov_b32_e32 v139, v233
	v_mov_b32_e32 v140, v234
	v_mov_b32_e32 v141, v235
	global_load_dwordx4 v[232:235], v[202:203], off offset:2064
	v_pk_add_f32 v[84:85], v[84:85], v[138:139]
	v_pk_add_f32 v[86:87], v[86:87], v[140:141]
	s_waitcnt vmcnt(7)
	v_mov_b32_e32 v80, v236
	v_mov_b32_e32 v81, v237
	v_mov_b32_e32 v82, v238
	v_mov_b32_e32 v83, v239
	global_load_dwordx4 v[236:239], v[204:205], off offset:2048
	v_pk_add_f32 v[150:151], v[90:91], v[80:81]
	v_add_co_u32_e32 v90, vcc, 0x3800000, v88
	v_pk_add_f32 v[98:99], v[98:99], v[82:83]
	s_nop 0
	v_addc_co_u32_e32 v91, vcc, 0, v89, vcc
	s_nop 0
	s_nop 0
	s_waitcnt vmcnt(7)
	v_mov_b32_e32 v142, v240
	v_mov_b32_e32 v143, v241
	v_mov_b32_e32 v144, v242
	v_mov_b32_e32 v145, v243
	global_load_dwordx4 v[240:243], v[204:205], off offset:2064
	v_pk_add_f32 v[84:85], v[84:85], v[142:143]
	v_pk_add_f32 v[86:87], v[86:87], v[144:145]
	s_waitcnt vmcnt(7)
	v_mov_b32_e32 v80, v244
	v_mov_b32_e32 v81, v245
	v_mov_b32_e32 v82, v246
	v_mov_b32_e32 v83, v247
	global_load_dwordx4 v[244:247], v[206:207], off offset:2048
	v_pk_add_f32 v[82:83], v[98:99], v[82:83]
	v_lshl_add_u64 v[98:99], v[88:89], 0, s[70:71]
	s_nop 0
	s_waitcnt vmcnt(7)
	v_mov_b32_e32 v146, v248
	v_mov_b32_e32 v147, v249
	v_mov_b32_e32 v148, v250
	v_mov_b32_e32 v149, v251
	global_load_dwordx4 v[248:251], v[206:207], off offset:2064
	v_pk_add_f32 v[86:87], v[86:87], v[148:149]
	v_pk_add_f32 v[84:85], v[84:85], v[146:147]
	v_pk_add_f32 v[80:81], v[150:151], v[80:81]
	s_waitcnt vmcnt(6)
	v_mov_b32_e32 v126, v228
	v_mov_b32_e32 v127, v229
	v_mov_b32_e32 v128, v230
	v_mov_b32_e32 v129, v231
	global_load_dwordx4 v[228:231], v[208:209], off offset:2048
	s_waitcnt vmcnt(6)
	v_mov_b32_e32 v130, v216
	v_mov_b32_e32 v131, v217
	v_mov_b32_e32 v132, v218
	v_mov_b32_e32 v133, v219
	global_load_dwordx4 v[216:219], v[208:209], off offset:2064
	v_pk_add_f32 v[136:137], v[126:127], v[130:131]
	v_lshl_add_u64 v[130:131], v[88:89], 0, s[74:75]
	v_pk_add_f32 v[134:135], v[128:129], v[132:133]
	s_nop 0
	s_waitcnt vmcnt(9)
	v_mov_b32_e32 v92, v224
	v_mov_b32_e32 v93, v225
	v_mov_b32_e32 v94, v226
	v_mov_b32_e32 v95, v227
	global_load_dwordx4 v[224:227], v[210:211], off offset:2048
	s_waitcnt vmcnt(7)
	v_mov_b32_e32 v96, v232
	v_mov_b32_e32 v97, v233
	v_mov_b32_e32 v98, v234
	v_mov_b32_e32 v99, v235
	global_load_dwordx4 v[232:235], v[210:211], off offset:2064
	v_pk_add_f32 v[92:93], v[92:93], v[96:97]
	v_pk_add_f32 v[94:95], v[94:95], v[98:99]
	s_waitcnt vmcnt(7)
	v_mov_b32_e32 v126, v236
	v_mov_b32_e32 v127, v237
	v_mov_b32_e32 v128, v238
	v_mov_b32_e32 v129, v239
	global_load_dwordx4 v[236:239], v[212:213], off offset:2048
	v_pk_add_f32 v[136:137], v[136:137], v[126:127]
	v_lshl_add_u64 v[126:127], v[88:89], 0, s[76:77]
	v_pk_add_f32 v[134:135], v[134:135], v[128:129]
	s_nop 0
	s_waitcnt vmcnt(7)
	v_mov_b32_e32 v130, v240
	v_mov_b32_e32 v131, v241
	v_mov_b32_e32 v132, v242
	v_mov_b32_e32 v133, v243
	global_load_dwordx4 v[240:243], v[212:213], off offset:2064
	v_pk_add_f32 v[92:93], v[92:93], v[130:131]
	v_pk_add_f32 v[94:95], v[94:95], v[132:133]
	s_waitcnt vmcnt(7)
	v_mov_b32_e32 v120, v244
	v_mov_b32_e32 v121, v245
	v_mov_b32_e32 v122, v246
	v_mov_b32_e32 v123, v247
	global_load_dwordx4 v[244:247], v[214:215], off offset:2048
	v_pk_add_f32 v[138:139], v[134:135], v[122:123]
	v_lshl_add_u64 v[134:135], v[88:89], 0, s[94:95]
	v_pk_add_f32 v[140:141], v[136:137], v[120:121]
	s_nop 0
	s_waitcnt vmcnt(7)
	v_mov_b32_e32 v126, v248
	v_mov_b32_e32 v127, v249
	v_mov_b32_e32 v128, v250
	v_mov_b32_e32 v129, v251
	global_load_dwordx4 v[248:251], v[214:215], off offset:2064
	v_pk_add_f32 v[92:93], v[92:93], v[126:127]
	v_pk_add_f32 v[94:95], v[94:95], v[128:129]
	s_waitcnt vmcnt(7)
	v_mov_b32_e32 v120, v228
	v_mov_b32_e32 v121, v229
	v_mov_b32_e32 v122, v230
	v_mov_b32_e32 v123, v231
	v_pk_add_f32 v[102:103], v[138:139], v[122:123]
	v_lshl_add_u64 v[138:139], v[88:89], 0, s[16:17]
	v_pk_add_f32 v[142:143], v[140:141], v[120:121]
	s_nop 0
	s_waitcnt vmcnt(6)
	v_mov_b32_e32 v134, v216
	v_mov_b32_e32 v135, v217
	v_mov_b32_e32 v136, v218
	v_mov_b32_e32 v137, v219
	v_pk_add_f32 v[92:93], v[92:93], v[134:135]
	v_pk_add_f32 v[94:95], v[94:95], v[136:137]
	s_waitcnt vmcnt(5)
	v_mov_b32_e32 v120, v224
	v_mov_b32_e32 v121, v225
	v_mov_b32_e32 v122, v226
	v_mov_b32_e32 v123, v227
	v_pk_add_f32 v[142:143], v[142:143], v[120:121]
	v_lshl_add_u64 v[120:121], v[88:89], 0, s[96:97]
	v_pk_add_f32 v[124:125], v[102:103], v[122:123]
	s_nop 0
	s_waitcnt vmcnt(4)
	v_mov_b32_e32 v138, v232
	v_mov_b32_e32 v139, v233
	v_mov_b32_e32 v140, v234
	v_mov_b32_e32 v141, v235
	v_pk_add_f32 v[92:93], v[92:93], v[138:139]
	v_pk_add_f32 v[94:95], v[94:95], v[140:141]
	s_waitcnt vmcnt(3)
	v_mov_b32_e32 v100, v236
	v_mov_b32_e32 v101, v237
	v_mov_b32_e32 v102, v238
	v_mov_b32_e32 v103, v239
	v_pk_add_f32 v[142:143], v[142:143], v[100:101]
	v_lshl_add_u64 v[100:101], v[88:89], 0, s[36:37]
	v_pk_add_f32 v[124:125], v[124:125], v[102:103]
	s_nop 0
	s_waitcnt vmcnt(2)
; __device__ __forceinline__ void phase_rows(const Params& p, const RowArgs& a, int G, int wave, int lane) {
;     ...
;                 const float* part = (const float*)p.out;
; #pragma unroll
;                 for (int u = 0; u < 2; ++u)
; #pragma unroll
;                     for (int j = 0; j < 4; ++j) { const float* pp = part + (size_t)(m0 + u - ML) * DM + 8 * lane + 512 * (j >> 1) + 4 * (j & 1); f32x4 s = *(const f32x4*)pp;
; #pragma unroll
;                         for (int k = 1; k < pg8::KSPLIT; ++k) s += *(const f32x4*)(pp + (size_t)k * MC * DM);
;                         y[u][j] = s; }
	v_mov_b32_e32 v120, v240
	v_mov_b32_e32 v121, v241
	v_mov_b32_e32 v122, v242
	v_mov_b32_e32 v123, v243
	v_pk_add_f32 v[92:93], v[92:93], v[120:121]
	v_lshl_add_u64 v[120:121], v[176:177], 0, s[22:23]
	v_pk_add_f32 v[94:95], v[94:95], v[122:123]
	v_add_co_u32_e32 v122, vcc, s55, v120
	v_lshl_add_u64 v[128:129], v[120:121], 0, s[24:25]
	s_nop 0
	v_addc_co_u32_e32 v123, vcc, 0, v121, vcc
	v_add_co_u32_e32 v132, vcc, s21, v120
	s_mov_b32 s21, 0x1800000
	s_nop 0
	v_addc_co_u32_e32 v133, vcc, 0, v121, vcc
	v_lshl_add_u64 v[140:141], v[120:121], 0, s[28:29]
	s_waitcnt vmcnt(1)
	v_mov_b32_e32 v88, v244
	v_mov_b32_e32 v89, v245
	v_mov_b32_e32 v90, v246
	v_mov_b32_e32 v91, v247
	v_pk_add_f32 v[90:91], v[124:125], v[90:91]
	s_waitcnt vmcnt(0)
	v_mov_b32_e32 v100, v248
	v_mov_b32_e32 v101, v249
	v_mov_b32_e32 v102, v250
	v_mov_b32_e32 v103, v251
	v_pk_add_f32 v[94:95], v[94:95], v[102:103]
	v_pk_add_f32 v[92:93], v[92:93], v[100:101]
	v_add_co_u32_e32 v200, vcc, 0x1000, v200
	s_nop 1
	v_addc_co_u32_e32 v201, vcc, 0, v201, vcc
	v_add_co_u32_e32 v202, vcc, 0x1000, v202
	s_nop 1
	v_addc_co_u32_e32 v203, vcc, 0, v203, vcc
	v_add_co_u32_e32 v204, vcc, 0x1000, v204
	s_nop 1
	v_addc_co_u32_e32 v205, vcc, 0, v205, vcc
	v_add_co_u32_e32 v206, vcc, 0x1000, v206
	s_nop 1
	v_addc_co_u32_e32 v207, vcc, 0, v207, vcc
	v_add_co_u32_e32 v208, vcc, 0x1000, v208
	s_nop 1
	v_addc_co_u32_e32 v209, vcc, 0, v209, vcc
	v_add_co_u32_e32 v210, vcc, 0x1000, v210
	s_nop 1
	v_addc_co_u32_e32 v211, vcc, 0, v211, vcc
	v_add_co_u32_e32 v212, vcc, 0x1000, v212
	s_nop 1
	v_addc_co_u32_e32 v213, vcc, 0, v213, vcc
	v_add_co_u32_e32 v214, vcc, 0x1000, v214
	s_nop 1
	v_addc_co_u32_e32 v215, vcc, 0, v215, vcc
	global_load_dwordx4 v[216:219], v[200:201], off offset:16
	global_load_dwordx4 v[224:227], v[200:201], off
	global_load_dwordx4 v[228:231], v[202:203], off
	global_load_dwordx4 v[232:235], v[202:203], off offset:16
	global_load_dwordx4 v[236:239], v[204:205], off
	global_load_dwordx4 v[240:243], v[204:205], off offset:16
	global_load_dwordx4 v[244:247], v[206:207], off
	global_load_dwordx4 v[248:251], v[206:207], off offset:16
	s_nop 0
	v_pk_add_f32 v[88:89], v[142:143], v[88:89]
	v_lshl_add_u64 v[142:143], v[120:121], 0, s[34:35]
	s_waitcnt vmcnt(6)
	v_mov_b32_e32 v96, v224
	v_mov_b32_e32 v97, v225
	v_mov_b32_e32 v98, v226
	v_mov_b32_e32 v99, v227
	global_load_dwordx4 v[224:227], v[208:209], off
	s_waitcnt vmcnt(6)
	v_mov_b32_e32 v124, v228
	v_mov_b32_e32 v125, v229
	v_mov_b32_e32 v126, v230
	v_mov_b32_e32 v127, v231
	global_load_dwordx4 v[228:231], v[208:209], off offset:16
	v_pk_add_f32 v[136:137], v[96:97], v[124:125]
	v_lshl_add_u64 v[124:125], v[120:121], 0, s[26:27]
	v_pk_add_f32 v[134:135], v[98:99], v[126:127]
	s_nop 0
	s_waitcnt vmcnt(9)
	v_mov_b32_e32 v100, v216
	v_mov_b32_e32 v101, v217
	v_mov_b32_e32 v102, v218
	v_mov_b32_e32 v103, v219
	global_load_dwordx4 v[216:219], v[210:211], off
	s_waitcnt vmcnt(7)
	v_mov_b32_e32 v128, v232
	v_mov_b32_e32 v129, v233
	v_mov_b32_e32 v130, v234
	v_mov_b32_e32 v131, v235
	global_load_dwordx4 v[232:235], v[210:211], off offset:16
	v_pk_add_f32 v[102:103], v[102:103], v[130:131]
	v_pk_add_f32 v[100:101], v[100:101], v[128:129]
	v_lshl_add_u64 v[128:129], v[120:121], 0, s[70:71]
	s_waitcnt vmcnt(7)
	v_mov_b32_e32 v96, v236
	v_mov_b32_e32 v97, v237
	v_mov_b32_e32 v98, v238
	v_mov_b32_e32 v99, v239
	global_load_dwordx4 v[236:239], v[212:213], off
	v_pk_add_f32 v[138:139], v[136:137], v[96:97]
	v_add_co_u32_e32 v136, vcc, s21, v120
	v_pk_add_f32 v[134:135], v[134:135], v[98:99]
	s_nop 0
	v_addc_co_u32_e32 v137, vcc, 0, v121, vcc
	s_brev_b32 s21, 64
	v_add_co_u32_e32 v140, vcc, s21, v120
	s_mov_b32 s21, 0x2800000
	s_nop 0
	v_addc_co_u32_e32 v141, vcc, 0, v121, vcc
	v_add_co_u32_e32 v144, vcc, s21, v120
	s_mov_b32 s21, 0x3000000
	s_nop 0
	v_addc_co_u32_e32 v145, vcc, 0, v121, vcc
	v_add_co_u32_e32 v148, vcc, s21, v120
	s_mov_b32 s21, 0x3800000
	s_nop 0
	v_addc_co_u32_e32 v149, vcc, 0, v121, vcc
	v_add_co_u32_e32 v152, vcc, s21, v120
	s_waitcnt vmcnt(7)
	v_mov_b32_e32 v124, v240
	v_mov_b32_e32 v125, v241
	v_mov_b32_e32 v126, v242
	v_mov_b32_e32 v127, v243
	global_load_dwordx4 v[240:243], v[212:213], off offset:16
	v_pk_add_f32 v[102:103], v[102:103], v[126:127]
	v_addc_co_u32_e32 v153, vcc, 0, v121, vcc
	v_pk_add_f32 v[100:101], v[100:101], v[124:125]
	s_waitcnt vmcnt(7)
	v_mov_b32_e32 v96, v244
	v_mov_b32_e32 v97, v245
	v_mov_b32_e32 v98, v246
	v_mov_b32_e32 v99, v247
	global_load_dwordx4 v[244:247], v[214:215], off
	v_pk_add_f32 v[134:135], v[134:135], v[98:99]
	v_pk_add_f32 v[138:139], v[138:139], v[96:97]
	v_lshl_add_u64 v[142:143], v[120:121], 0, s[62:63]
	s_waitcnt vmcnt(7)
	v_mov_b32_e32 v178, v248
	v_mov_b32_e32 v179, v249
	v_mov_b32_e32 v180, v250
	v_mov_b32_e32 v181, v251
	global_load_dwordx4 v[248:251], v[214:215], off offset:16
	v_pk_add_f32 v[102:103], v[102:103], v[180:181]
	v_pk_add_f32 v[100:101], v[100:101], v[178:179]
	s_waitcnt vmcnt(7)
	v_mov_b32_e32 v96, v224
	v_mov_b32_e32 v97, v225
	v_mov_b32_e32 v98, v226
	v_mov_b32_e32 v99, v227
	global_load_dwordx4 v[224:227], v[200:201], off offset:2064
	v_pk_add_f32 v[134:135], v[134:135], v[98:99]
	v_pk_add_f32 v[138:139], v[138:139], v[96:97]
	v_lshl_add_u64 v[142:143], v[120:121], 0, s[64:65]
	s_waitcnt vmcnt(7)
	v_mov_b32_e32 v182, v228
	v_mov_b32_e32 v183, v229
	v_mov_b32_e32 v184, v230
	v_mov_b32_e32 v185, v231
	global_load_dwordx4 v[228:231], v[200:201], off offset:2048
	v_pk_add_f32 v[102:103], v[102:103], v[184:185]
	v_pk_add_f32 v[100:101], v[100:101], v[182:183]
	s_waitcnt vmcnt(7)
; __device__ __forceinline__ void phase_rows(const Params& p, const RowArgs& a, int G, int wave, int lane) {
;     ...
;                 const float* part = (const float*)p.out;
; #pragma unroll
;                 for (int u = 0; u < 2; ++u)
; #pragma unroll
;                     for (int j = 0; j < 4; ++j) { const float* pp = part + (size_t)(m0 + u - ML) * DM + 8 * lane + 512 * (j >> 1) + 4 * (j & 1); f32x4 s = *(const f32x4*)pp;
; #pragma unroll
;                         for (int k = 1; k < pg8::KSPLIT; ++k) s += *(const f32x4*)(pp + (size_t)k * MC * DM);
;                         y[u][j] = s; }
	v_mov_b32_e32 v96, v216
	v_mov_b32_e32 v97, v217
	v_mov_b32_e32 v98, v218
	v_mov_b32_e32 v99, v219
	global_load_dwordx4 v[216:219], v[202:203], off offset:2048
	v_pk_add_f32 v[134:135], v[134:135], v[98:99]
	v_pk_add_f32 v[138:139], v[138:139], v[96:97]
	v_lshl_add_u64 v[142:143], v[120:121], 0, s[68:69]
	s_waitcnt vmcnt(7)
	v_mov_b32_e32 v186, v232
	v_mov_b32_e32 v187, v233
	v_mov_b32_e32 v188, v234
	v_mov_b32_e32 v189, v235
	global_load_dwordx4 v[232:235], v[202:203], off offset:2064
	v_pk_add_f32 v[102:103], v[102:103], v[188:189]
	v_pk_add_f32 v[100:101], v[100:101], v[186:187]
	s_waitcnt vmcnt(7)
	v_mov_b32_e32 v96, v236
	v_mov_b32_e32 v97, v237
	v_mov_b32_e32 v98, v238
	v_mov_b32_e32 v99, v239
	global_load_dwordx4 v[236:239], v[204:205], off offset:2048
	v_pk_add_f32 v[134:135], v[134:135], v[98:99]
	v_pk_add_f32 v[138:139], v[138:139], v[96:97]
	s_nop 0
	s_waitcnt vmcnt(7)
	v_mov_b32_e32 v190, v240
	v_mov_b32_e32 v191, v241
	v_mov_b32_e32 v192, v242
	v_mov_b32_e32 v193, v243
	global_load_dwordx4 v[240:243], v[204:205], off offset:2064
	v_pk_add_f32 v[102:103], v[102:103], v[192:193]
	v_pk_add_f32 v[100:101], v[100:101], v[190:191]
	s_waitcnt vmcnt(7)
	v_mov_b32_e32 v96, v244
	v_mov_b32_e32 v97, v245
	v_mov_b32_e32 v98, v246
	v_mov_b32_e32 v99, v247
	global_load_dwordx4 v[244:247], v[206:207], off offset:2048
	v_pk_add_f32 v[98:99], v[134:135], v[98:99]
	v_lshl_add_u64 v[134:135], v[120:121], 0, s[74:75]
	v_pk_add_f32 v[96:97], v[138:139], v[96:97]
	s_waitcnt vmcnt(5)
	v_mov_b32_e32 v178, v228
	v_mov_b32_e32 v179, v229
	v_mov_b32_e32 v180, v230
	v_mov_b32_e32 v181, v231
	global_load_dwordx4 v[228:231], v[206:207], off offset:2064
	s_waitcnt vmcnt(5)
	v_mov_b32_e32 v182, v216
	v_mov_b32_e32 v183, v217
	v_mov_b32_e32 v184, v218
	v_mov_b32_e32 v185, v219
	global_load_dwordx4 v[216:219], v[208:209], off offset:2048
	v_pk_add_f32 v[122:123], v[180:181], v[184:185]
	v_pk_add_f32 v[138:139], v[178:179], v[182:183]
	s_nop 0
	s_waitcnt vmcnt(8)
	v_mov_b32_e32 v124, v224
	v_mov_b32_e32 v125, v225
	v_mov_b32_e32 v126, v226
	v_mov_b32_e32 v127, v227
	global_load_dwordx4 v[224:227], v[208:209], off offset:2064
	s_waitcnt vmcnt(6)
	v_mov_b32_e32 v128, v232
	v_mov_b32_e32 v129, v233
	v_mov_b32_e32 v130, v234
	v_mov_b32_e32 v131, v235
	global_load_dwordx4 v[232:235], v[210:211], off offset:2048
	v_pk_add_f32 v[126:127], v[126:127], v[130:131]
	v_pk_add_f32 v[124:125], v[124:125], v[128:129]
	s_waitcnt vmcnt(11)
	v_mov_b32_e32 v194, v248
	v_mov_b32_e32 v195, v249
	v_mov_b32_e32 v196, v250
	v_mov_b32_e32 v197, v251
	global_load_dwordx4 v[248:251], v[210:211], off offset:2064
	v_pk_add_f32 v[102:103], v[102:103], v[196:197]
	v_pk_add_f32 v[100:101], v[100:101], v[194:195]
	s_waitcnt vmcnt(7)
	v_mov_b32_e32 v178, v236
	v_mov_b32_e32 v179, v237
	v_mov_b32_e32 v180, v238
	v_mov_b32_e32 v181, v239
	global_load_dwordx4 v[236:239], v[212:213], off offset:2048
	v_pk_add_f32 v[142:143], v[138:139], v[178:179]
	v_lshl_add_u64 v[138:139], v[120:121], 0, s[76:77]
	v_pk_add_f32 v[122:123], v[122:123], v[180:181]
	s_nop 0
	s_waitcnt vmcnt(7)
	v_mov_b32_e32 v132, v240
	v_mov_b32_e32 v133, v241
	v_mov_b32_e32 v134, v242
	v_mov_b32_e32 v135, v243
	global_load_dwordx4 v[240:243], v[212:213], off offset:2064
	v_pk_add_f32 v[126:127], v[126:127], v[134:135]
	v_pk_add_f32 v[124:125], v[124:125], v[132:133]
	s_waitcnt vmcnt(7)
	v_mov_b32_e32 v178, v244
	v_mov_b32_e32 v179, v245
	v_mov_b32_e32 v180, v246
	v_mov_b32_e32 v181, v247
	global_load_dwordx4 v[244:247], v[214:215], off offset:2048
	v_pk_add_f32 v[146:147], v[142:143], v[178:179]
	v_lshl_add_u64 v[142:143], v[120:121], 0, s[94:95]
	v_pk_add_f32 v[122:123], v[122:123], v[180:181]
	s_nop 0
	s_waitcnt vmcnt(7)
	v_mov_b32_e32 v136, v228
	v_mov_b32_e32 v137, v229
	v_mov_b32_e32 v138, v230
	v_mov_b32_e32 v139, v231
	global_load_dwordx4 v[228:231], v[214:215], off offset:2064
	v_pk_add_f32 v[126:127], v[126:127], v[138:139]
	v_pk_add_f32 v[124:125], v[124:125], v[136:137]
	v_readlane_b32 s94, v255, 27
	v_readlane_b32 s95, v255, 28
	s_waitcnt vmcnt(7)
	v_mov_b32_e32 v178, v216
	v_mov_b32_e32 v179, v217
	v_mov_b32_e32 v180, v218
	v_mov_b32_e32 v181, v219
	v_pk_add_f32 v[150:151], v[146:147], v[178:179]
	v_lshl_add_u64 v[146:147], v[120:121], 0, s[16:17]
	v_pk_add_f32 v[122:123], v[122:123], v[180:181]
	s_nop 0
	s_waitcnt vmcnt(6)
	v_mov_b32_e32 v140, v224
	v_mov_b32_e32 v141, v225
	v_mov_b32_e32 v142, v226
	v_mov_b32_e32 v143, v227
	v_pk_add_f32 v[126:127], v[126:127], v[142:143]
	v_pk_add_f32 v[124:125], v[124:125], v[140:141]
	s_waitcnt vmcnt(5)
	v_mov_b32_e32 v178, v232
	v_mov_b32_e32 v179, v233
	v_mov_b32_e32 v180, v234
	v_mov_b32_e32 v181, v235
	v_pk_add_f32 v[154:155], v[150:151], v[178:179]
	v_lshl_add_u64 v[150:151], v[120:121], 0, s[96:97]
	v_pk_add_f32 v[122:123], v[122:123], v[180:181]
	s_nop 0
	s_waitcnt vmcnt(4)
	v_mov_b32_e32 v144, v248
	v_mov_b32_e32 v145, v249
	v_mov_b32_e32 v146, v250
	v_mov_b32_e32 v147, v251
	v_pk_add_f32 v[126:127], v[126:127], v[146:147]
	v_pk_add_f32 v[124:125], v[124:125], v[144:145]
	s_mov_b32 s96, s38
	s_waitcnt vmcnt(3)
	v_mov_b32_e32 v180, v236
	v_mov_b32_e32 v181, v237
	v_mov_b32_e32 v182, v238
	v_mov_b32_e32 v183, v239
	v_pk_add_f32 v[180:181], v[154:155], v[180:181]
	v_lshl_add_u64 v[154:155], v[120:121], 0, s[36:37]
	v_pk_add_f32 v[178:179], v[122:123], v[182:183]
	s_nop 0
	s_waitcnt vmcnt(2)
	v_mov_b32_e32 v148, v240
	v_mov_b32_e32 v149, v241
	v_mov_b32_e32 v150, v242
	v_mov_b32_e32 v151, v243
	v_pk_add_f32 v[126:127], v[126:127], v[150:151]
	v_pk_add_f32 v[124:125], v[124:125], v[148:149]
	s_waitcnt vmcnt(1)
	v_mov_b32_e32 v120, v244
	v_mov_b32_e32 v121, v245
	v_mov_b32_e32 v122, v246
	v_mov_b32_e32 v123, v247
	v_pk_add_f32 v[122:123], v[178:179], v[122:123]
	v_pk_add_f32 v[120:121], v[180:181], v[120:121]
	s_waitcnt vmcnt(0)
	v_mov_b32_e32 v152, v228
	v_mov_b32_e32 v153, v229
	v_mov_b32_e32 v154, v230
	v_mov_b32_e32 v155, v231
	v_pk_add_f32 v[126:127], v[126:127], v[154:155]
	v_pk_add_f32 v[124:125], v[124:125], v[152:153]
